# v020 + batched LRU gate-weight staging (3 load rounds instead of 16) + P1 row remap so each batch's waves sweep contiguous memory
# speedup vs baseline: 1.0058x; 1.0058x over previous
.LBB0_52:
	s_and_b32 s70, s20, 63
	s_lshl_b32 s70, s70, 2
	s_lshl_b32 s71, s21, 6
	s_add_u32 s70, s70, s71
	s_lshr_b32 s71, s20, 6
	s_lshl_b32 s71, s71, 11
	s_add_u32 s22, s70, s71
	s_mov_b32 s23, 0
	s_lshl_b64 s[30:31], s[22:23], 12
	v_lshl_add_u64 v[32:33], v[106:107], 0, s[30:31]
	global_load_dwordx4 v[92:95], v[32:33], off nt
	global_load_dwordx4 v[88:91], v[32:33], off offset:1024 nt
	global_load_dwordx4 v[80:83], v[32:33], off offset:3072 nt
	global_load_dwordx4 v[84:87], v[32:33], off offset:2048 nt
	v_add_co_u32_e32 v34, vcc, 0x1000, v32
	s_lshl_b64 s[30:31], s[22:23], 11
	s_nop 0
	v_addc_co_u32_e32 v35, vcc, 0, v33, vcc
	global_load_dwordx4 v[76:79], v[34:35], off nt
	global_load_dwordx4 v[72:75], v[34:35], off offset:1024 nt
	global_load_dwordx4 v[64:67], v[34:35], off offset:3072 nt
	global_load_dwordx4 v[68:71], v[34:35], off offset:2048 nt
	v_add_co_u32_e32 v34, vcc, 0x2000, v32
	s_mov_b32 s29, 0
	s_nop 0
	v_addc_co_u32_e32 v35, vcc, 0, v33, vcc
	global_load_dwordx4 v[60:63], v[34:35], off nt
	global_load_dwordx4 v[56:59], v[34:35], off offset:1024 nt
	global_load_dwordx4 v[48:51], v[34:35], off offset:3072 nt
	global_load_dwordx4 v[52:55], v[34:35], off offset:2048 nt
	v_add_co_u32_e32 v32, vcc, s26, v32
	s_waitcnt vmcnt(11)
	v_pk_mul_f32 v[134:135], v[94:95], v[94:95]
	v_addc_co_u32_e32 v33, vcc, 0, v33, vcc
	global_load_dwordx4 v[44:47], v[32:33], off nt
	global_load_dwordx4 v[40:43], v[32:33], off offset:1024 nt
	global_load_dwordx4 v[36:39], v[32:33], off offset:2048 nt
	s_nop 0
	global_load_dwordx4 v[32:35], v[32:33], off offset:3072 nt
	v_pk_mul_f32 v[136:137], v[92:93], v[92:93]
	s_waitcnt vmcnt(14)
	v_pk_mul_f32 v[138:139], v[90:91], v[90:91]
	v_pk_mul_f32 v[140:141], v[88:89], v[88:89]
	s_waitcnt vmcnt(13)
	v_mul_f32_e32 v145, v82, v82
	s_waitcnt vmcnt(12)
	v_mul_f32_e32 v142, v85, v85
	v_mul_f32_e32 v144, v87, v87
	v_mul_f32_e32 v148, v83, v83
	v_pk_mov_b32 v[146:147], v[136:137], v[134:135] op_sel:[1,0]
	v_mov_b32_e32 v137, v135
	v_pk_mov_b32 v[134:135], v[140:141], v[138:139] op_sel:[1,0]
	v_mov_b32_e32 v141, v139
	v_pk_fma_f32 v[138:139], v[84:85], v[84:85], v[142:143] op_sel_hi:[1,1,0]
	v_pk_fma_f32 v[142:143], v[86:87], v[86:87], v[144:145] op_sel_hi:[1,1,0]
	v_pk_add_f32 v[136:137], v[146:147], v[136:137]
	v_pk_add_f32 v[134:135], v[134:135], v[140:141]
	v_mov_b32_e32 v139, v145
	v_mov_b32_e32 v143, v148
	s_waitcnt vmcnt(11)
	v_pk_mul_f32 v[140:141], v[78:79], v[78:79]
	v_pk_mul_f32 v[144:145], v[76:77], v[76:77]
	s_waitcnt vmcnt(10)
	v_pk_mul_f32 v[146:147], v[74:75], v[74:75]
	v_pk_mul_f32 v[148:149], v[72:73], v[72:73]
	v_pk_add_f32 v[138:139], v[138:139], v[142:143]
	v_pk_mov_b32 v[142:143], v[144:145], v[140:141] op_sel:[1,0]
	v_mov_b32_e32 v145, v141
	v_pk_mov_b32 v[140:141], v[148:149], v[146:147] op_sel:[1,0]
	v_mov_b32_e32 v149, v147
	v_mul_f32_e32 v156, v80, v80
	v_mul_f32_e32 v157, v81, v81
	s_waitcnt vmcnt(8)
	v_mul_f32_e32 v150, v69, v69
	v_mul_f32_e32 v152, v71, v71
	v_pk_add_f32 v[136:137], v[136:137], v[136:137] op_sel:[0,1] op_sel_hi:[1,0]
	v_pk_add_f32 v[134:135], v[134:135], v[134:135] op_sel:[0,1] op_sel_hi:[1,0]
	v_pk_add_f32 v[142:143], v[142:143], v[144:145]
	v_pk_add_f32 v[140:141], v[140:141], v[148:149]
	v_mul_f32_e32 v158, v66, v66
	v_mul_f32_e32 v159, v67, v67
	v_mul_f32_e32 v160, v64, v64
	v_mul_f32_e32 v161, v65, v65
	v_pk_fma_f32 v[150:151], v[68:69], v[68:69], v[150:151] op_sel_hi:[1,1,0]
	v_pk_fma_f32 v[152:153], v[70:71], v[70:71], v[152:153] op_sel_hi:[1,1,0]
	v_mov_b32_e32 v137, v156
	v_mov_b32_e32 v135, v157
	v_pk_add_f32 v[142:143], v[142:143], v[142:143] op_sel:[0,1] op_sel_hi:[1,0]
	v_pk_add_f32 v[140:141], v[140:141], v[140:141] op_sel:[0,1] op_sel_hi:[1,0]
	s_waitcnt vmcnt(7)
	v_pk_mul_f32 v[146:147], v[62:63], v[62:63]
	v_pk_mul_f32 v[154:155], v[60:61], v[60:61]
	v_mov_b32_e32 v151, v158
	v_mov_b32_e32 v153, v159
	v_pk_add_f32 v[134:135], v[136:137], v[134:135]
	v_mov_b32_e32 v143, v160
	v_mov_b32_e32 v141, v161
	v_pk_mov_b32 v[144:145], v[154:155], v[146:147] op_sel:[1,0]
	v_mov_b32_e32 v155, v147
	v_pk_add_f32 v[136:137], v[150:151], v[152:153]
	v_pk_add_f32 v[134:135], v[134:135], v[138:139]
	v_pk_add_f32 v[138:139], v[142:143], v[140:141]
	s_waitcnt vmcnt(6)
	v_pk_mul_f32 v[140:141], v[58:59], v[58:59]
	v_pk_mul_f32 v[142:143], v[56:57], v[56:57]
	v_pk_add_f32 v[136:137], v[138:139], v[136:137]
	v_pk_add_f32 v[138:139], v[144:145], v[154:155]
	v_pk_mov_b32 v[144:145], v[142:143], v[140:141] op_sel:[1,0]
	v_mov_b32_e32 v143, v141
	v_pk_add_f32 v[140:141], v[144:145], v[142:143]
	s_waitcnt vmcnt(5)
	v_mul_f32_e32 v142, v48, v48
	v_mul_f32_e32 v143, v49, v49
	v_pk_add_f32 v[138:139], v[138:139], v[138:139] op_sel:[0,1] op_sel_hi:[1,0]
	v_pk_add_f32 v[140:141], v[140:141], v[140:141] op_sel:[0,1] op_sel_hi:[1,0]
	v_mov_b32_e32 v139, v142
	v_mov_b32_e32 v141, v143
	v_pk_add_f32 v[138:139], v[138:139], v[140:141]
	s_waitcnt vmcnt(4)
	v_mul_f32_e32 v140, v53, v53
	v_mul_f32_e32 v142, v55, v55
	v_mul_f32_e32 v144, v50, v50
	v_mul_f32_e32 v145, v51, v51
	v_pk_fma_f32 v[140:141], v[52:53], v[52:53], v[140:141] op_sel_hi:[1,1,0]
	v_pk_fma_f32 v[142:143], v[54:55], v[54:55], v[142:143] op_sel_hi:[1,1,0]
	v_mov_b32_e32 v141, v144
	v_mov_b32_e32 v143, v145
	v_mov_b32_e32 v144, v136
	v_mov_b32_e32 v145, v134
	v_mov_b32_e32 v134, v137
	v_pk_add_f32 v[134:135], v[144:145], v[134:135]
	ds_bpermute_b32 v137, v125, v135
	ds_bpermute_b32 v136, v125, v134
	v_pk_add_f32 v[140:141], v[140:141], v[142:143]
	s_waitcnt vmcnt(3)
	v_pk_mul_f32 v[142:143], v[44:45], v[44:45]
	v_pk_add_f32 v[138:139], v[138:139], v[140:141]
	v_pk_mul_f32 v[140:141], v[46:47], v[46:47]
	s_waitcnt lgkmcnt(0)
	v_pk_add_f32 v[134:135], v[134:135], v[136:137]
	ds_bpermute_b32 v137, v126, v135
	ds_bpermute_b32 v136, v126, v134
	v_pk_mov_b32 v[144:145], v[142:143], v[140:141] op_sel:[1,0]
	v_mov_b32_e32 v143, v141
	v_pk_add_f32 v[140:141], v[144:145], v[142:143]
	s_waitcnt vmcnt(2)
	v_pk_mul_f32 v[142:143], v[42:43], v[42:43]
	s_waitcnt lgkmcnt(0)
	v_pk_add_f32 v[134:135], v[134:135], v[136:137]
	ds_bpermute_b32 v137, v127, v135
	ds_bpermute_b32 v136, v127, v134
	v_pk_mul_f32 v[144:145], v[40:41], v[40:41]
	v_pk_add_f32 v[140:141], v[140:141], v[140:141] op_sel:[0,1] op_sel_hi:[1,0]
	v_pk_mov_b32 v[146:147], v[144:145], v[142:143] op_sel:[1,0]
	v_mov_b32_e32 v145, v143
	s_waitcnt lgkmcnt(0)
	v_pk_add_f32 v[134:135], v[134:135], v[136:137]
	ds_bpermute_b32 v137, v128, v135
	ds_bpermute_b32 v136, v128, v134
	v_pk_add_f32 v[142:143], v[146:147], v[144:145]
	s_waitcnt vmcnt(0)
	v_mul_f32_e32 v144, v32, v32
	v_mul_f32_e32 v145, v33, v33
	v_pk_add_f32 v[142:143], v[142:143], v[142:143] op_sel:[0,1] op_sel_hi:[1,0]
	s_waitcnt lgkmcnt(0)
	v_pk_add_f32 v[134:135], v[134:135], v[136:137]
	ds_bpermute_b32 v137, v129, v135
	ds_bpermute_b32 v136, v129, v134
	v_mov_b32_e32 v141, v144
	v_mov_b32_e32 v143, v145
	v_pk_add_f32 v[140:141], v[140:141], v[142:143]
	v_mul_f32_e32 v142, v37, v37
	s_waitcnt lgkmcnt(0)
	v_pk_add_f32 v[134:135], v[134:135], v[136:137]
	ds_bpermute_b32 v137, v130, v135
	ds_bpermute_b32 v136, v130, v134
	v_mul_f32_e32 v144, v39, v39
	v_mul_f32_e32 v146, v34, v34
	v_mul_f32_e32 v147, v35, v35
	v_pk_fma_f32 v[142:143], v[36:37], v[36:37], v[142:143] op_sel_hi:[1,1,0]
	v_pk_fma_f32 v[144:145], v[38:39], v[38:39], v[144:145] op_sel_hi:[1,1,0]
	s_waitcnt lgkmcnt(0)
	v_pk_add_f32 v[134:135], v[134:135], v[136:137]
	v_mov_b64_e32 v[136:137], s[18:19]
	v_mov_b32_e32 v143, v146
	v_mov_b32_e32 v145, v147
	v_pk_fma_f32 v[134:135], v[134:135], s[16:17], v[136:137] op_sel_hi:[1,0,0]
	v_pk_add_f32 v[142:143], v[142:143], v[144:145]
	v_mul_f32_e32 v144, 0x4b800000, v135
	v_cmp_gt_f32_e32 vcc, s28, v135
	v_pk_add_f32 v[140:141], v[140:141], v[142:143]
	v_lshl_add_u64 v[142:143], v[100:101], 0, s[30:31]
	v_cndmask_b32_e32 v135, v135, v144, vcc
	v_rsq_f32_e32 v135, v135
	s_nop 0
	v_mul_f32_e32 v144, 0x45800000, v135
	v_cndmask_b32_e32 v144, v135, v144, vcc
	v_pk_mul_f32 v[80:81], v[80:81], v[144:145] op_sel_hi:[1,0]
	v_pk_mul_f32 v[84:85], v[84:85], v[144:145] op_sel_hi:[1,0]
	v_pk_fma_f32 v[80:81], v[118:119], v[80:81], v[28:29]
	v_pk_mul_f32 v[86:87], v[86:87], v[144:145] op_sel_hi:[1,0]
	v_cvt_pk_bf16_f32 v80, v80, v81
	v_mul_f32_e32 v81, 0x4b800000, v134
	v_cmp_gt_f32_e32 vcc, s28, v134
	v_pk_fma_f32 v[86:87], v[108:109], v[86:87], v[18:19]
	v_pk_fma_f32 v[84:85], v[112:113], v[84:85], v[16:17]
	v_pk_mul_f32 v[82:83], v[82:83], v[144:145] op_sel_hi:[1,0]
	v_cndmask_b32_e32 v81, v134, v81, vcc
	v_pk_mul_f32 v[92:93], v[92:93], v[144:145] op_sel_hi:[1,0]
	v_pk_mul_f32 v[94:95], v[94:95], v[144:145] op_sel_hi:[1,0]
	v_cvt_pk_bf16_f32 v84, v84, v85
	v_cvt_pk_bf16_f32 v85, v86, v87
	v_pk_fma_f32 v[82:83], v[116:117], v[82:83], v[30:31]
	v_rsq_f32_e32 v86, v81
	v_pk_fma_f32 v[94:95], v[120:121], v[94:95], v[26:27]
	v_pk_fma_f32 v[92:93], v[122:123], v[92:93], v[24:25]
	v_cvt_pk_bf16_f32 v81, v82, v83
	v_mov_b32_e32 v82, v140
	v_mov_b32_e32 v83, v138
	v_mov_b32_e32 v138, v141
	v_cvt_pk_bf16_f32 v92, v92, v93
	v_cvt_pk_bf16_f32 v93, v94, v95
	v_add_u32_e32 v94, s25, v97
	v_pk_add_f32 v[82:83], v[82:83], v[138:139]
	global_store_dwordx2 v[142:143], v[84:85], off offset:1024
	ds_write2st64_b64 v94, v[84:85], v[80:81] offset0:2 offset1:3
	ds_bpermute_b32 v85, v125, v83
	ds_bpermute_b32 v84, v125, v82
	global_store_dwordx2 v[142:143], v[80:81], off offset:1536
	v_mul_f32_e32 v80, 0x45800000, v86
	v_cndmask_b32_e32 v80, v86, v80, vcc
	v_pk_mul_f32 v[76:77], v[76:77], v[80:81] op_sel_hi:[1,0]
	v_pk_mul_f32 v[78:79], v[78:79], v[80:81] op_sel_hi:[1,0]
	v_pk_fma_f32 v[76:77], v[122:123], v[76:77], v[24:25]
	v_pk_fma_f32 v[78:79], v[120:121], v[78:79], v[26:27]
	v_cvt_pk_bf16_f32 v76, v76, v77
	v_cvt_pk_bf16_f32 v77, v78, v79
	s_waitcnt lgkmcnt(0)
	v_pk_add_f32 v[78:79], v[82:83], v[84:85]
	ds_bpermute_b32 v83, v126, v79
	ds_bpermute_b32 v82, v126, v78
	v_pk_mul_f32 v[72:73], v[72:73], v[80:81] op_sel_hi:[1,0]
	v_pk_mul_f32 v[74:75], v[74:75], v[80:81] op_sel_hi:[1,0]
	v_pk_fma_f32 v[72:73], v[114:115], v[72:73], v[20:21]
	v_pk_fma_f32 v[74:75], v[110:111], v[74:75], v[22:23]
	s_waitcnt lgkmcnt(0)
	v_pk_add_f32 v[78:79], v[78:79], v[82:83]
	ds_bpermute_b32 v83, v127, v79
	ds_bpermute_b32 v82, v127, v78
	v_cvt_pk_bf16_f32 v72, v72, v73
	v_cvt_pk_bf16_f32 v73, v74, v75
	v_add_u32_e32 v81, 16, v94
	global_store_dwordx2 v[142:143], v[72:73], off offset:2560
	ds_write2st64_b64 v81, v[76:77], v[72:73] offset0:4 offset1:5
	s_waitcnt lgkmcnt(1)
	v_pk_add_f32 v[72:73], v[78:79], v[82:83]
	ds_bpermute_b32 v75, v128, v73
	ds_bpermute_b32 v74, v128, v72
	v_pk_mul_f32 v[68:69], v[68:69], v[80:81] op_sel_hi:[1,0]
	v_pk_mul_f32 v[70:71], v[70:71], v[80:81] op_sel_hi:[1,0]
	v_pk_fma_f32 v[68:69], v[112:113], v[68:69], v[16:17]
	v_pk_fma_f32 v[70:71], v[108:109], v[70:71], v[18:19]
	s_waitcnt lgkmcnt(0)
	v_pk_add_f32 v[72:73], v[72:73], v[74:75]
	ds_bpermute_b32 v75, v129, v73
	ds_bpermute_b32 v74, v129, v72
	v_cvt_pk_bf16_f32 v68, v68, v69
	v_cvt_pk_bf16_f32 v69, v70, v71
	v_pk_mul_f32 v[64:65], v[64:65], v[80:81] op_sel_hi:[1,0]
	v_pk_mul_f32 v[66:67], v[66:67], v[80:81] op_sel_hi:[1,0]
	s_waitcnt lgkmcnt(0)
	v_pk_add_f32 v[70:71], v[72:73], v[74:75]
	ds_bpermute_b32 v73, v130, v71
	ds_bpermute_b32 v72, v130, v70
	v_pk_fma_f32 v[64:65], v[118:119], v[64:65], v[28:29]
	v_pk_fma_f32 v[66:67], v[116:117], v[66:67], v[30:31]
	v_cvt_pk_bf16_f32 v64, v64, v65
	v_pk_mul_f32 v[88:89], v[88:89], v[144:145] op_sel_hi:[1,0]
	s_waitcnt lgkmcnt(0)
	v_pk_add_f32 v[70:71], v[70:71], v[72:73]
	v_pk_mul_f32 v[90:91], v[90:91], v[144:145] op_sel_hi:[1,0]
	v_pk_fma_f32 v[70:71], v[70:71], s[16:17], v[136:137] op_sel_hi:[1,0,0]
	v_pk_fma_f32 v[90:91], v[110:111], v[90:91], v[22:23]
	v_mul_f32_e32 v65, 0x4b800000, v71
	v_cmp_gt_f32_e32 vcc, s28, v71
	v_pk_fma_f32 v[88:89], v[114:115], v[88:89], v[20:21]
	global_store_dwordx2 v[142:143], v[92:93], off
	v_cndmask_b32_e32 v65, v71, v65, vcc
	v_rsq_f32_e32 v71, v65
	v_cvt_pk_bf16_f32 v65, v66, v67
	global_store_dwordx2 v[142:143], v[64:65], off offset:3584
	ds_write2st64_b64 v81, v[68:69], v[64:65] offset0:6 offset1:7
	v_mul_f32_e32 v64, 0x45800000, v71
	v_cndmask_b32_e32 v64, v71, v64, vcc
	v_pk_mul_f32 v[60:61], v[60:61], v[64:65] op_sel_hi:[1,0]
	v_pk_mul_f32 v[62:63], v[62:63], v[64:65] op_sel_hi:[1,0]
	v_pk_fma_f32 v[60:61], v[122:123], v[60:61], v[24:25]
	v_pk_fma_f32 v[62:63], v[120:121], v[62:63], v[26:27]
	v_cvt_pk_bf16_f32 v60, v60, v61
	v_cvt_pk_bf16_f32 v61, v62, v63
	v_add_co_u32_e32 v62, vcc, s27, v142
	v_pk_mul_f32 v[48:49], v[48:49], v[64:65] op_sel_hi:[1,0]
	s_nop 0
	v_addc_co_u32_e32 v63, vcc, 0, v143, vcc
	v_pk_fma_f32 v[48:49], v[118:119], v[48:49], v[28:29]
	v_pk_mul_f32 v[52:53], v[52:53], v[64:65] op_sel_hi:[1,0]
	v_pk_mul_f32 v[54:55], v[54:55], v[64:65] op_sel_hi:[1,0]
	v_cvt_pk_bf16_f32 v48, v48, v49
	v_mul_f32_e32 v49, 0x4b800000, v70
	v_cmp_gt_f32_e32 vcc, s28, v70
	v_pk_fma_f32 v[54:55], v[108:109], v[54:55], v[18:19]
	v_pk_fma_f32 v[52:53], v[112:113], v[52:53], v[16:17]
	v_cndmask_b32_e32 v49, v70, v49, vcc
	v_cvt_pk_bf16_f32 v52, v52, v53
	v_cvt_pk_bf16_f32 v53, v54, v55
	v_rsq_f32_e32 v54, v49
	v_pk_mul_f32 v[56:57], v[56:57], v[64:65] op_sel_hi:[1,0]
	v_pk_mul_f32 v[58:59], v[58:59], v[64:65] op_sel_hi:[1,0]
	v_pk_mul_f32 v[50:51], v[50:51], v[64:65] op_sel_hi:[1,0]
	v_pk_fma_f32 v[58:59], v[110:111], v[58:59], v[22:23]
	v_pk_fma_f32 v[56:57], v[114:115], v[56:57], v[20:21]
	v_pk_fma_f32 v[50:51], v[116:117], v[50:51], v[30:31]
	v_cvt_pk_bf16_f32 v56, v56, v57
	v_cvt_pk_bf16_f32 v57, v58, v59
	v_add_u32_e32 v58, 32, v94
	v_cvt_pk_bf16_f32 v49, v50, v51
	global_store_dwordx2 v[62:63], v[48:49], off offset:1536
	ds_write2st64_b64 v58, v[52:53], v[48:49] offset0:10 offset1:11
	v_mul_f32_e32 v48, 0x45800000, v54
	v_cndmask_b32_e32 v48, v54, v48, vcc
	v_pk_mul_f32 v[44:45], v[44:45], v[48:49] op_sel_hi:[1,0]
	v_pk_mul_f32 v[46:47], v[46:47], v[48:49] op_sel_hi:[1,0]
	v_pk_mul_f32 v[40:41], v[40:41], v[48:49] op_sel_hi:[1,0]
	v_pk_mul_f32 v[42:43], v[42:43], v[48:49] op_sel_hi:[1,0]
	v_pk_mul_f32 v[36:37], v[36:37], v[48:49] op_sel_hi:[1,0]
	v_pk_mul_f32 v[38:39], v[38:39], v[48:49] op_sel_hi:[1,0]
	v_pk_mul_f32 v[32:33], v[32:33], v[48:49] op_sel_hi:[1,0]
	v_pk_mul_f32 v[34:35], v[34:35], v[48:49] op_sel_hi:[1,0]
	v_pk_fma_f32 v[46:47], v[120:121], v[46:47], v[26:27]
	v_pk_fma_f32 v[44:45], v[122:123], v[44:45], v[24:25]
	v_pk_fma_f32 v[42:43], v[110:111], v[42:43], v[22:23]
	v_pk_fma_f32 v[40:41], v[114:115], v[40:41], v[20:21]
	v_pk_fma_f32 v[38:39], v[108:109], v[38:39], v[18:19]
	v_pk_fma_f32 v[36:37], v[112:113], v[36:37], v[16:17]
	v_pk_fma_f32 v[34:35], v[116:117], v[34:35], v[30:31]
	v_pk_fma_f32 v[32:33], v[118:119], v[32:33], v[28:29]
	v_cvt_pk_bf16_f32 v88, v88, v89
	v_cvt_pk_bf16_f32 v89, v90, v91
	v_cvt_pk_bf16_f32 v44, v44, v45
	v_cvt_pk_bf16_f32 v45, v46, v47
	v_cvt_pk_bf16_f32 v40, v40, v41
	v_cvt_pk_bf16_f32 v41, v42, v43
	v_add_u32_e32 v42, 48, v94
	v_cvt_pk_bf16_f32 v36, v36, v37
	v_cvt_pk_bf16_f32 v37, v38, v39
	v_cvt_pk_bf16_f32 v32, v32, v33
	v_cvt_pk_bf16_f32 v33, v34, v35
	global_store_dwordx2 v[142:143], v[88:89], off offset:512
	ds_write2st64_b64 v94, v[92:93], v[88:89] offset1:1
	global_store_dwordx2 v[142:143], v[76:77], off offset:2048
	global_store_dwordx2 v[142:143], v[68:69], off offset:3072
	global_store_dwordx2 v[62:63], v[60:61], off
	global_store_dwordx2 v[62:63], v[56:57], off offset:512
	ds_write2st64_b64 v58, v[60:61], v[56:57] offset0:8 offset1:9
	global_store_dwordx2 v[62:63], v[52:53], off offset:1024
	global_store_dwordx2 v[62:63], v[44:45], off offset:2048
	global_store_dwordx2 v[62:63], v[40:41], off offset:2560
	ds_write2st64_b64 v42, v[44:45], v[40:41] offset0:12 offset1:13
	global_store_dwordx2 v[62:63], v[36:37], off offset:3072
	global_store_dwordx2 v[62:63], v[32:33], off offset:3584
	ds_write2st64_b64 v42, v[36:37], v[32:33] offset0:14 offset1:15
	s_waitcnt lgkmcnt(0)
	v_mov_b32_e32 v32, 0
	v_mov_b32_e32 v33, v32
	v_mov_b32_e32 v34, v32
	v_mov_b32_e32 v35, v32

.LBB0_578:
	v_mov_b32_e32 v152, v188
	v_lshlrev_b64 v[8:9], 2, v[152:153]
	v_lshl_add_u64 v[10:11], s[6:7], 0, v[8:9]
	v_lshl_add_u64 v[12:13], s[44:45], 0, v[8:9]
	global_load_dword v16, v[10:11], off
	global_load_dword v17, v[10:11], off offset:512
	global_load_dword v18, v[10:11], off offset:1024
	global_load_dword v19, v[10:11], off offset:1536
	global_load_dword v20, v[10:11], off offset:2048
	global_load_dword v21, v[10:11], off offset:2560
	global_load_dword v22, v[10:11], off offset:3072
	global_load_dword v23, v[10:11], off offset:3584
	global_load_dword v24, v[12:13], off
	global_load_dword v25, v[12:13], off offset:512
	global_load_dword v26, v[12:13], off offset:1024
	global_load_dword v27, v[12:13], off offset:1536
	global_load_dword v28, v[12:13], off offset:2048
	global_load_dword v29, v[12:13], off offset:2560
	global_load_dword v30, v[12:13], off offset:3072
	global_load_dword v31, v[12:13], off offset:3584
	v_add_u32_e32 v152, 0x800, v188
	v_lshlrev_b64 v[8:9], 2, v[152:153]
	v_lshl_add_u64 v[10:11], s[6:7], 0, v[8:9]
	v_lshl_add_u64 v[12:13], s[44:45], 0, v[8:9]
	global_load_dword v32, v[10:11], off
	global_load_dword v33, v[10:11], off offset:512
	global_load_dword v34, v[10:11], off offset:1024
	global_load_dword v35, v[10:11], off offset:1536
	global_load_dword v36, v[10:11], off offset:2048
	global_load_dword v37, v[10:11], off offset:2560
	global_load_dword v38, v[10:11], off offset:3072
	global_load_dword v39, v[10:11], off offset:3584
	global_load_dword v40, v[12:13], off
	global_load_dword v41, v[12:13], off offset:512
	global_load_dword v42, v[12:13], off offset:1024
	global_load_dword v43, v[12:13], off offset:1536
	global_load_dword v44, v[12:13], off offset:2048
	global_load_dword v45, v[12:13], off offset:2560
	global_load_dword v46, v[12:13], off offset:3072
	global_load_dword v47, v[12:13], off offset:3584
	v_add_u32_e32 v152, 0x1000, v188
	v_lshlrev_b64 v[8:9], 2, v[152:153]
	v_lshl_add_u64 v[10:11], s[6:7], 0, v[8:9]
	v_lshl_add_u64 v[12:13], s[44:45], 0, v[8:9]
	global_load_dword v48, v[10:11], off
	global_load_dword v49, v[10:11], off offset:512
	global_load_dword v50, v[10:11], off offset:1024
	global_load_dword v51, v[10:11], off offset:1536
	global_load_dword v52, v[10:11], off offset:2048
	global_load_dword v53, v[10:11], off offset:2560
	global_load_dword v54, v[10:11], off offset:3072
	global_load_dword v55, v[10:11], off offset:3584
	global_load_dword v56, v[12:13], off
	global_load_dword v57, v[12:13], off offset:512
	global_load_dword v58, v[12:13], off offset:1024
	global_load_dword v59, v[12:13], off offset:1536
	global_load_dword v60, v[12:13], off offset:2048
	global_load_dword v61, v[12:13], off offset:2560
	global_load_dword v62, v[12:13], off offset:3072
	global_load_dword v63, v[12:13], off offset:3584
	s_waitcnt vmcnt(0)
	v_cvt_pk_bf16_f32 v4, v16, v17
	v_cvt_pk_bf16_f32 v5, v18, v19
	v_cvt_pk_bf16_f32 v6, v20, v21
	v_cvt_pk_bf16_f32 v7, v22, v23
	ds_write_b128 v2, v[4:7]
	v_cvt_pk_bf16_f32 v144, v24, v25
	v_cvt_pk_bf16_f32 v145, v26, v27
	v_cvt_pk_bf16_f32 v146, v28, v29
	v_cvt_pk_bf16_f32 v147, v30, v31
	ds_write_b128 v2, v[144:147] offset:8192
	v_cvt_pk_bf16_f32 v4, v32, v33
	v_cvt_pk_bf16_f32 v5, v34, v35
	v_cvt_pk_bf16_f32 v6, v36, v37
	v_cvt_pk_bf16_f32 v7, v38, v39
	ds_write_b128 v2, v[4:7] offset:1024
	v_cvt_pk_bf16_f32 v144, v40, v41
	v_cvt_pk_bf16_f32 v145, v42, v43
	v_cvt_pk_bf16_f32 v146, v44, v45
	v_cvt_pk_bf16_f32 v147, v46, v47
	ds_write_b128 v2, v[144:147] offset:9216
	v_cvt_pk_bf16_f32 v4, v48, v49
	v_cvt_pk_bf16_f32 v5, v50, v51
	v_cvt_pk_bf16_f32 v6, v52, v53
	v_cvt_pk_bf16_f32 v7, v54, v55
	ds_write_b128 v2, v[4:7] offset:2048
	v_cvt_pk_bf16_f32 v144, v56, v57
	v_cvt_pk_bf16_f32 v145, v58, v59
	v_cvt_pk_bf16_f32 v146, v60, v61
	v_cvt_pk_bf16_f32 v147, v62, v63
	ds_write_b128 v2, v[144:147] offset:10240
	v_add_u32_e32 v152, 0x1800, v188
	v_lshlrev_b64 v[8:9], 2, v[152:153]
	v_lshl_add_u64 v[10:11], s[6:7], 0, v[8:9]
	v_lshl_add_u64 v[12:13], s[44:45], 0, v[8:9]
	global_load_dword v16, v[10:11], off
	global_load_dword v17, v[10:11], off offset:512
	global_load_dword v18, v[10:11], off offset:1024
	global_load_dword v19, v[10:11], off offset:1536
	global_load_dword v20, v[10:11], off offset:2048
	global_load_dword v21, v[10:11], off offset:2560
	global_load_dword v22, v[10:11], off offset:3072
	global_load_dword v23, v[10:11], off offset:3584
	global_load_dword v24, v[12:13], off
	global_load_dword v25, v[12:13], off offset:512
	global_load_dword v26, v[12:13], off offset:1024
	global_load_dword v27, v[12:13], off offset:1536
	global_load_dword v28, v[12:13], off offset:2048
	global_load_dword v29, v[12:13], off offset:2560
	global_load_dword v30, v[12:13], off offset:3072
	global_load_dword v31, v[12:13], off offset:3584
	v_add_u32_e32 v152, 0x2000, v188
	v_lshlrev_b64 v[8:9], 2, v[152:153]
	v_lshl_add_u64 v[10:11], s[6:7], 0, v[8:9]
	v_lshl_add_u64 v[12:13], s[44:45], 0, v[8:9]
	global_load_dword v32, v[10:11], off
	global_load_dword v33, v[10:11], off offset:512
	global_load_dword v34, v[10:11], off offset:1024
	global_load_dword v35, v[10:11], off offset:1536
	global_load_dword v36, v[10:11], off offset:2048
	global_load_dword v37, v[10:11], off offset:2560
	global_load_dword v38, v[10:11], off offset:3072
	global_load_dword v39, v[10:11], off offset:3584
	global_load_dword v40, v[12:13], off
	global_load_dword v41, v[12:13], off offset:512
	global_load_dword v42, v[12:13], off offset:1024
	global_load_dword v43, v[12:13], off offset:1536
	global_load_dword v44, v[12:13], off offset:2048
	global_load_dword v45, v[12:13], off offset:2560
	global_load_dword v46, v[12:13], off offset:3072
	global_load_dword v47, v[12:13], off offset:3584
	v_add_u32_e32 v152, 0x2800, v188
	v_lshlrev_b64 v[8:9], 2, v[152:153]
	v_lshl_add_u64 v[10:11], s[6:7], 0, v[8:9]
	v_lshl_add_u64 v[12:13], s[44:45], 0, v[8:9]
	global_load_dword v48, v[10:11], off
	global_load_dword v49, v[10:11], off offset:512
	global_load_dword v50, v[10:11], off offset:1024
	global_load_dword v51, v[10:11], off offset:1536
	global_load_dword v52, v[10:11], off offset:2048
	global_load_dword v53, v[10:11], off offset:2560
	global_load_dword v54, v[10:11], off offset:3072
	global_load_dword v55, v[10:11], off offset:3584
	global_load_dword v56, v[12:13], off
	global_load_dword v57, v[12:13], off offset:512
	global_load_dword v58, v[12:13], off offset:1024
	global_load_dword v59, v[12:13], off offset:1536
	global_load_dword v60, v[12:13], off offset:2048
	global_load_dword v61, v[12:13], off offset:2560
	global_load_dword v62, v[12:13], off offset:3072
	global_load_dword v63, v[12:13], off offset:3584
	s_waitcnt vmcnt(0)
	v_cvt_pk_bf16_f32 v4, v16, v17
	v_cvt_pk_bf16_f32 v5, v18, v19
	v_cvt_pk_bf16_f32 v6, v20, v21
	v_cvt_pk_bf16_f32 v7, v22, v23
	ds_write_b128 v2, v[4:7] offset:3072
	v_cvt_pk_bf16_f32 v144, v24, v25
	v_cvt_pk_bf16_f32 v145, v26, v27
	v_cvt_pk_bf16_f32 v146, v28, v29
	v_cvt_pk_bf16_f32 v147, v30, v31
	ds_write_b128 v2, v[144:147] offset:11264
	v_cvt_pk_bf16_f32 v4, v32, v33
	v_cvt_pk_bf16_f32 v5, v34, v35
	v_cvt_pk_bf16_f32 v6, v36, v37
	v_cvt_pk_bf16_f32 v7, v38, v39
	ds_write_b128 v2, v[4:7] offset:4096
	v_cvt_pk_bf16_f32 v144, v40, v41
	v_cvt_pk_bf16_f32 v145, v42, v43
	v_cvt_pk_bf16_f32 v146, v44, v45
	v_cvt_pk_bf16_f32 v147, v46, v47
	ds_write_b128 v2, v[144:147] offset:12288
	v_cvt_pk_bf16_f32 v4, v48, v49
	v_cvt_pk_bf16_f32 v5, v50, v51
	v_cvt_pk_bf16_f32 v6, v52, v53
	v_cvt_pk_bf16_f32 v7, v54, v55
	ds_write_b128 v2, v[4:7] offset:5120
	v_cvt_pk_bf16_f32 v144, v56, v57
	v_cvt_pk_bf16_f32 v145, v58, v59
	v_cvt_pk_bf16_f32 v146, v60, v61
	v_cvt_pk_bf16_f32 v147, v62, v63
	ds_write_b128 v2, v[144:147] offset:13312
	v_add_u32_e32 v152, 0x3000, v188
	v_lshlrev_b64 v[8:9], 2, v[152:153]
	v_lshl_add_u64 v[10:11], s[6:7], 0, v[8:9]
	v_lshl_add_u64 v[12:13], s[44:45], 0, v[8:9]
	global_load_dword v16, v[10:11], off
	global_load_dword v17, v[10:11], off offset:512
	global_load_dword v18, v[10:11], off offset:1024
	global_load_dword v19, v[10:11], off offset:1536
	global_load_dword v20, v[10:11], off offset:2048
	global_load_dword v21, v[10:11], off offset:2560
	global_load_dword v22, v[10:11], off offset:3072
	global_load_dword v23, v[10:11], off offset:3584
	global_load_dword v24, v[12:13], off
	global_load_dword v25, v[12:13], off offset:512
	global_load_dword v26, v[12:13], off offset:1024
	global_load_dword v27, v[12:13], off offset:1536
	global_load_dword v28, v[12:13], off offset:2048
	global_load_dword v29, v[12:13], off offset:2560
	global_load_dword v30, v[12:13], off offset:3072
	global_load_dword v31, v[12:13], off offset:3584
	v_add_u32_e32 v152, 0x3800, v188
	v_lshlrev_b64 v[8:9], 2, v[152:153]
	v_lshl_add_u64 v[10:11], s[6:7], 0, v[8:9]
	v_lshl_add_u64 v[12:13], s[44:45], 0, v[8:9]
	global_load_dword v32, v[10:11], off
	global_load_dword v33, v[10:11], off offset:512
	global_load_dword v34, v[10:11], off offset:1024
	global_load_dword v35, v[10:11], off offset:1536
	global_load_dword v36, v[10:11], off offset:2048
	global_load_dword v37, v[10:11], off offset:2560
	global_load_dword v38, v[10:11], off offset:3072
	global_load_dword v39, v[10:11], off offset:3584
	global_load_dword v40, v[12:13], off
	global_load_dword v41, v[12:13], off offset:512
	global_load_dword v42, v[12:13], off offset:1024
	global_load_dword v43, v[12:13], off offset:1536
	global_load_dword v44, v[12:13], off offset:2048
	global_load_dword v45, v[12:13], off offset:2560
	global_load_dword v46, v[12:13], off offset:3072
	global_load_dword v47, v[12:13], off offset:3584
	s_waitcnt vmcnt(0)
	v_cvt_pk_bf16_f32 v4, v16, v17
	v_cvt_pk_bf16_f32 v5, v18, v19
	v_cvt_pk_bf16_f32 v6, v20, v21
	v_cvt_pk_bf16_f32 v7, v22, v23
	ds_write_b128 v2, v[4:7] offset:6144
	v_cvt_pk_bf16_f32 v144, v24, v25
	v_cvt_pk_bf16_f32 v145, v26, v27
	v_cvt_pk_bf16_f32 v146, v28, v29
	v_cvt_pk_bf16_f32 v147, v30, v31
	ds_write_b128 v2, v[144:147] offset:14336
	v_cvt_pk_bf16_f32 v4, v32, v33
	v_cvt_pk_bf16_f32 v5, v34, v35
	v_cvt_pk_bf16_f32 v6, v36, v37
	v_cvt_pk_bf16_f32 v7, v38, v39
	ds_write_b128 v2, v[4:7] offset:7168
	v_cvt_pk_bf16_f32 v144, v40, v41
	v_cvt_pk_bf16_f32 v145, v42, v43
	v_cvt_pk_bf16_f32 v146, v44, v45
	v_cvt_pk_bf16_f32 v147, v46, v47
	ds_write_b128 v2, v[144:147] offset:15360
	s_lshl_b32 s12, s29, 7
	v_add_u32_e32 v96, s12, v186
	v_ashrrev_i32_e32 v97, 31, v96
	v_readlane_b32 s60, v254, 0
	v_lshlrev_b64 v[4:5], 2, v[96:97]
	v_readlane_b32 s61, v254, 1
	v_readlane_b32 s62, v254, 2
	v_readlane_b32 s63, v254, 3
	v_readlane_b32 s64, v254, 4
	v_readlane_b32 s65, v254, 5
	v_readlane_b32 s66, v254, 6
	v_readlane_b32 s67, v254, 7
	v_readlane_b32 s68, v254, 8
	v_readlane_b32 s69, v254, 9
	v_readlane_b32 s70, v254, 10
	v_readlane_b32 s71, v254, 11
	v_readlane_b32 s72, v254, 12
	v_readlane_b32 s73, v254, 13
	v_readlane_b32 s74, v254, 14
	v_readlane_b32 s75, v254, 15
	s_waitcnt lgkmcnt(0)
	s_mov_b32 s6, 0xc1a00000
	s_nop 0
	v_lshl_add_u64 v[0:1], s[74:75], 0, v[4:5]
	v_readlane_b32 s60, v254, 34
	v_readlane_b32 s64, v254, 38
	v_readlane_b32 s65, v254, 39
	v_readlane_b32 s62, v254, 36
	v_readlane_b32 s63, v254, 37
	v_lshl_add_u64 v[2:3], s[64:65], 0, v[4:5]
	global_load_dword v3, v[2:3], off
	v_lshl_add_u64 v[4:5], s[62:63], 0, v[4:5]
	global_load_dword v0, v[0:1], off
	v_readlane_b32 s61, v254, 35
	global_load_dword v1, v[4:5], off
	ds_read_b128 v[32:35], v187
	ds_read_b128 v[36:39], v187 offset:1024
	ds_read_b128 v[40:43], v187 offset:2048
	ds_read_b128 v[44:47], v187 offset:3072
	ds_read_b128 v[48:51], v187 offset:4096
	ds_read_b128 v[52:55], v187 offset:5120
	ds_read_b128 v[56:59], v187 offset:6144
	ds_read_b128 v[60:63], v187 offset:7168
	ds_read_b128 v[64:67], v187 offset:8192
	ds_read_b128 v[68:71], v187 offset:9216
	ds_read_b128 v[72:75], v187 offset:10240
	ds_read_b128 v[76:79], v187 offset:11264
	ds_read_b128 v[80:83], v187 offset:12288
	ds_read_b128 v[84:87], v187 offset:13312
	ds_read_b128 v[88:91], v187 offset:14336
	ds_read_b128 v[92:95], v187 offset:15360
	v_readlane_b32 s66, v254, 40
	v_readlane_b32 s67, v254, 41
	v_readlane_b32 s68, v254, 42
	v_readlane_b32 s69, v254, 43
	v_readlane_b32 s70, v254, 44
	v_readlane_b32 s71, v254, 45
	v_readlane_b32 s72, v254, 46
	v_readlane_b32 s73, v254, 47
	v_readlane_b32 s74, v254, 48
	v_readlane_b32 s75, v254, 49
	s_waitcnt vmcnt(0)
	v_xor_b32_e32 v2, 0x80000000, v3
	v_cmp_ngt_f32_e32 vcc, s6, v3
	s_and_saveexec_b64 s[6:7], vcc
	s_cbranch_execz .LBB0_581
	v_mul_f32_e32 v2, 0xbfb8aa3b, v3
	v_exp_f32_e32 v16, v2
	s_mov_b32 s20, 0x3f2aaaab
	v_add_f32_e32 v4, 1.0, v16
	v_frexp_mant_f32_e32 v6, v4
	v_cvt_f64_f32_e32 v[2:3], v4
	v_frexp_exp_i32_f64_e32 v2, v[2:3]
	v_cmp_gt_f32_e32 vcc, s20, v6
	v_add_f32_e32 v5, -1.0, v4
	v_sub_f32_e32 v7, v5, v4
	v_subbrev_co_u32_e32 v10, vcc, 0, v2, vcc
	v_sub_u32_e32 v2, 0, v10
	v_sub_f32_e32 v5, v16, v5
	v_add_f32_e32 v7, 1.0, v7
	v_ldexp_f32 v3, v4, v2
	v_add_f32_e32 v5, v5, v7
	v_add_f32_e32 v4, -1.0, v3
	v_add_f32_e32 v6, 1.0, v3
	v_ldexp_f32 v2, v5, v2
	v_add_f32_e32 v5, 1.0, v4
	v_add_f32_e32 v7, -1.0, v6
	v_sub_f32_e32 v5, v3, v5
	v_sub_f32_e32 v3, v3, v7
	v_add_f32_e32 v5, v2, v5
	v_add_f32_e32 v2, v2, v3
	v_add_f32_e32 v11, v6, v2
	v_rcp_f32_e32 v13, v11
	v_sub_f32_e32 v3, v11, v6
	v_sub_f32_e32 v12, v2, v3
	v_add_f32_e32 v3, v4, v5
	v_mul_f32_e32 v15, v3, v13
	v_sub_f32_e32 v2, v3, v4
	v_mul_f32_e32 v4, v11, v15
	v_fma_f32 v6, v15, v11, -v4
	v_fmac_f32_e32 v6, v15, v12
	v_sub_f32_e32 v14, v5, v2
	v_add_f32_e32 v2, v4, v6
	v_sub_f32_e32 v5, v3, v2
	v_pk_add_f32 v[8:9], v[2:3], v[4:5] neg_lo:[0,1] neg_hi:[0,1]
	v_mov_b32_e32 v7, v2
	v_pk_add_f32 v[2:3], v[8:9], v[6:7] neg_lo:[0,1] neg_hi:[0,1]
	s_mov_b32 s20, 0x3f317218
	v_add_f32_e32 v3, v14, v3
	v_add_f32_e32 v2, v2, v3
	v_add_f32_e32 v3, v5, v2
	v_mul_f32_e32 v14, v13, v3
	v_mul_f32_e32 v4, v11, v14
	v_fma_f32 v6, v14, v11, -v4
	v_fmac_f32_e32 v6, v14, v12
	v_sub_f32_e32 v5, v5, v3
	v_add_f32_e32 v11, v2, v5
	v_add_f32_e32 v2, v4, v6
	v_sub_f32_e32 v5, v3, v2
	v_pk_add_f32 v[8:9], v[2:3], v[4:5] neg_lo:[0,1] neg_hi:[0,1]
	v_mov_b32_e32 v7, v2
	v_pk_add_f32 v[2:3], v[8:9], v[6:7] neg_lo:[0,1] neg_hi:[0,1]
	s_nop 0
	v_add_f32_e32 v3, v11, v3
	v_add_f32_e32 v2, v2, v3
	v_add_f32_e32 v3, v15, v14
	v_add_f32_e32 v2, v5, v2
	v_sub_f32_e32 v4, v3, v15
	v_mul_f32_e32 v2, v13, v2
	v_sub_f32_e32 v4, v14, v4
	v_add_f32_e32 v4, v4, v2
	v_add_f32_e32 v6, v3, v4
	v_mul_f32_e32 v7, v6, v6
	v_fmamk_f32 v2, v7, 0x3e9b6dac, v189
	v_fmaak_f32 v159, v7, v2, 0x3f2aaada
	v_cvt_f32_i32_e32 v2, v10
	v_sub_f32_e32 v3, v6, v3
	v_sub_f32_e32 v3, v4, v3
	v_ldexp_f32 v8, v3, 1
	v_mul_f32_e32 v3, v6, v7
	v_ldexp_f32 v5, v6, 1
	v_pk_mul_f32 v[6:7], v[2:3], v[158:159]
	s_nop 0
	v_fma_f32 v4, v2, s20, -v6
	v_fmac_f32_e32 v4, 0xb102e308, v2
	v_pk_add_f32 v[2:3], v[6:7], v[4:5]
	s_mov_b32 s20, 0x7f800000
	v_sub_f32_e32 v5, v3, v5
	v_sub_f32_e32 v5, v7, v5
	v_add_f32_e32 v9, v8, v5
	v_mov_b32_e32 v8, v6
	v_pk_add_f32 v[6:7], v[2:3], v[6:7] neg_lo:[0,1] neg_hi:[0,1]
	v_pk_add_f32 v[10:11], v[2:3], v[8:9]
	v_mov_b32_e32 v5, v2
	v_mov_b32_e32 v7, v11
	v_pk_add_f32 v[12:13], v[4:5], v[6:7] neg_lo:[0,1] neg_hi:[0,1]
	v_pk_add_f32 v[4:5], v[4:5], v[6:7]
	v_mov_b32_e32 v8, v9
	v_pk_add_f32 v[6:7], v[4:5], v[2:3] op_sel:[1,0] op_sel_hi:[0,1] neg_lo:[0,1] neg_hi:[0,1]
	v_pk_add_f32 v[14:15], v[10:11], v[6:7] op_sel_hi:[1,0] neg_lo:[0,1] neg_hi:[0,1]
	v_mov_b32_e32 v10, v11
	v_mov_b32_e32 v11, v5
	v_pk_mov_b32 v[6:7], v[2:3], v[6:7] op_sel:[1,0]
	v_mov_b32_e32 v9, v2
	v_pk_add_f32 v[6:7], v[10:11], v[6:7] neg_lo:[0,1] neg_hi:[0,1]
	v_mov_b32_e32 v14, v12
	v_pk_add_f32 v[2:3], v[8:9], v[6:7] neg_lo:[0,1] neg_hi:[0,1]
	v_mov_b32_e32 v13, v5
	v_pk_add_f32 v[6:7], v[14:15], v[2:3]
	v_cmp_neq_f32_e32 vcc, s20, v16
	v_pk_add_f32 v[8:9], v[6:7], v[6:7] op_sel:[0,1] op_sel_hi:[1,0]
	s_mov_b32 s20, 0x33800000
	v_pk_add_f32 v[4:5], v[4:5], v[8:9] op_sel:[1,0] op_sel_hi:[0,1]
	v_mov_b32_e32 v7, v4
	v_pk_add_f32 v[10:11], v[6:7], v[12:13] neg_lo:[0,1] neg_hi:[0,1]
	v_mov_b32_e32 v3, v8
	v_sub_f32_e32 v5, v6, v10
	v_pk_add_f32 v[2:3], v[2:3], v[10:11] neg_lo:[0,1] neg_hi:[0,1]
	v_sub_f32_e32 v5, v12, v5
	v_add_f32_e32 v2, v2, v5
	v_add_f32_e32 v2, v2, v3
	v_add_f32_e32 v2, v4, v2
	v_cndmask_b32_e32 v2, v190, v2, vcc
	v_cmp_ngt_f32_e32 vcc, -1.0, v16
	s_nop 1
	v_cndmask_b32_e32 v2, v191, v2, vcc
	v_cmp_neq_f32_e32 vcc, -1.0, v16
	s_nop 1
	v_cndmask_b32_e32 v2, v192, v2, vcc
	v_cmp_lt_f32_e64 vcc, |v16|, s20
	s_nop 1
	v_cndmask_b32_e32 v2, v2, v16, vcc
